# C5 + attention score section: key batches 1-3 prefetched into own registers AND rel-pos-bias values fetched in one LDS burst into the (dead) score registers, fma+select per element
# speedup vs baseline: 1.0029x; 1.0029x over previous
; __device__ __forceinline__ f32x4 mfma16(bf16x8 a, bf16x8 b, f32x4 c) { return __builtin_amdgcn_mfma_f32_16x16x32_bf16(a, b, c, 0, 0, 0); }
; __device__ __forceinline__ void phase_attn(const Args& a, unsigned char* smem, int tid, int lane, int wave, bf16_t* Yout) {
;     ...
;                     const float* rp = rpb_s + (rs + i - r + 7) * 31;
; #pragma unroll
;                     for (int hf = 0; hf < 2; ++hf) {
;                         f32x4 s = {0.f, 0.f, 0.f, 0.f};
;                         s = mfma16(kbuf[0][(ii * 2 + hf) * 2], qf0, s); s = mfma16(kbuf[0][(ii * 2 + hf) * 2 + 1], qf1, s);
; #pragma unroll
;                         for (int e = 0; e < 4; ++e) { const int kc = kc0 + 8 * g + 4 * hf + e; const bool ok = (kc >= cs) && (kc < cs + 16);
;                             const int dc = min(max(kc - qc + 15, 0), 30);
;                             s[e] = ok ? s[e] * 0.125f + rp[dc] : -1e30f; }
;                         st[i * 2 + hf] = s;
;                     }
.LBB0_351:
	s_or_b64 exec, exec, s[38:39]
	v_mov_b32_e32 v227, 0xf149f2ca
	v_add_u32_e32 v24, 15, v38
	v_min_u32_e32 v24, 30, v24
	v_lshl_add_u32 v24, v24, 2, s1
	v_add_u32_e32 v25, 15, v39
	v_min_u32_e32 v25, 30, v25
	v_lshl_add_u32 v25, v25, 2, s1
	v_add_u32_e32 v26, 15, v40
	v_min_u32_e32 v26, 30, v26
	v_lshl_add_u32 v26, v26, 2, s1
	v_add_u32_e32 v27, 15, v41
	v_min_u32_e32 v27, 30, v27
	v_lshl_add_u32 v27, v27, 2, s1
	v_add_u32_e32 v28, 15, v42
	v_min_u32_e32 v28, 30, v28
	v_lshl_add_u32 v28, v28, 2, s1
	v_add_u32_e32 v29, 15, v43
	v_min_u32_e32 v29, 30, v29
	v_lshl_add_u32 v29, v29, 2, s1
	v_add_u32_e32 v30, 15, v44
	v_min_u32_e32 v30, 30, v30
	v_lshl_add_u32 v30, v30, 2, s1
	v_add_u32_e32 v31, 15, v45
	v_min_u32_e32 v31, 30, v31
	v_lshl_add_u32 v31, v31, 2, s1
	ds_read_b32 v77, v24 offset:992
	ds_read_b32 v76, v25 offset:992
	ds_read_b32 v79, v26 offset:992
	ds_read_b32 v78, v27 offset:992
	ds_read_b32 v81, v28 offset:992
	ds_read_b32 v80, v29 offset:992
	ds_read_b32 v83, v30 offset:992
	ds_read_b32 v82, v31 offset:992
	ds_read_b32 v85, v24 offset:1116
	ds_read_b32 v84, v25 offset:1116
	ds_read_b32 v87, v26 offset:1116
	ds_read_b32 v86, v27 offset:1116
	s_waitcnt lgkmcnt(3)
	ds_read_b32 v89, v28 offset:1116
	ds_read_b32 v88, v29 offset:1116
	ds_read_b32 v91, v30 offset:1116
	ds_read_b32 v90, v31 offset:1116
	ds_read_b32 v93, v24 offset:1240
	ds_read_b32 v92, v25 offset:1240
	ds_read_b32 v95, v26 offset:1240
	ds_read_b32 v94, v27 offset:1240
	ds_read_b32 v97, v28 offset:1240
	ds_read_b32 v96, v29 offset:1240
	ds_read_b32 v99, v30 offset:1240
	ds_read_b32 v98, v31 offset:1240
	s_waitcnt lgkmcnt(3)
	ds_read_b32 v101, v24 offset:1364
	ds_read_b32 v100, v25 offset:1364
	ds_read_b32 v103, v26 offset:1364
	ds_read_b32 v102, v27 offset:1364
	ds_read_b32 v105, v28 offset:1364
	ds_read_b32 v104, v29 offset:1364
	ds_read_b32 v107, v30 offset:1364
	ds_read_b32 v106, v31 offset:1364
	ds_read_b32 v109, v24 offset:1488
	ds_read_b32 v108, v25 offset:1488
	ds_read_b32 v111, v26 offset:1488
	ds_read_b32 v110, v27 offset:1488
	s_waitcnt lgkmcnt(3)
	ds_read_b32 v148, v28 offset:1488
	ds_read_b32 v147, v29 offset:1488
	ds_read_b32 v150, v30 offset:1488
	ds_read_b32 v149, v31 offset:1488
	ds_read_b32 v152, v24 offset:1612
	ds_read_b32 v151, v25 offset:1612
	ds_read_b32 v154, v26 offset:1612
	ds_read_b32 v153, v27 offset:1612
	ds_read_b32 v216, v28 offset:1612
	ds_read_b32 v155, v29 offset:1612
	ds_read_b32 v218, v30 offset:1612
	ds_read_b32 v217, v31 offset:1612
	s_waitcnt lgkmcnt(3)
	ds_read_b32 v220, v24 offset:1736
	ds_read_b32 v219, v25 offset:1736
	ds_read_b32 v222, v26 offset:1736
	ds_read_b32 v221, v27 offset:1736
	ds_read_b32 v224, v28 offset:1736
	ds_read_b32 v223, v29 offset:1736
	ds_read_b32 v226, v30 offset:1736
	s_waitcnt vmcnt(19)
	v_mfma_f32_16x16x32_bf16 v[20:23], v[20:23], v[4:7], 0
	s_waitcnt vmcnt(18)
	v_mfma_f32_16x16x32_bf16 v[16:19], v[16:19], v[0:3], v[20:23]
	s_waitcnt lgkmcnt(0)
	s_nop 6
	v_fmac_f32_e32 v77, 0x3e000000, v16
	v_cndmask_b32_e64 v77, v227, v77, s[22:23]
	v_fmac_f32_e32 v76, 0x3e000000, v17
	v_cndmask_b32_e64 v76, v227, v76, s[24:25]
	v_fmac_f32_e32 v79, 0x3e000000, v18
	v_cndmask_b32_e64 v79, v227, v79, s[26:27]
	v_fmac_f32_e32 v78, 0x3e000000, v19
	v_cndmask_b32_e64 v78, v227, v78, s[28:29]
	s_waitcnt vmcnt(17)
	v_mfma_f32_16x16x32_bf16 v[12:15], v[12:15], v[4:7], 0
	s_waitcnt vmcnt(16)
	v_mfma_f32_16x16x32_bf16 v[8:11], v[8:11], v[0:3], v[12:15]
	s_nop 7
	v_fmac_f32_e32 v81, 0x3e000000, v8
	v_cndmask_b32_e64 v81, v227, v81, s[30:31]
	v_fmac_f32_e32 v80, 0x3e000000, v9
	v_cndmask_b32_e64 v80, v227, v80, s[34:35]
	v_fmac_f32_e32 v83, 0x3e000000, v10
	v_cndmask_b32_e64 v83, v227, v83, s[36:37]
	v_fmac_f32_e32 v82, 0x3e000000, v11
	v_cndmask_b32_e64 v82, v227, v82, s[6:7]
	s_add_i32 s38, s12, 0x180
	s_mov_b32 s39, s13
	v_lshl_add_u64 v[12:13], v[36:37], 0, s[38:39]
	s_add_i32 s38, s12, 0x1c0
	v_lshlrev_b64 v[12:13], 11, v[12:13]
	v_lshl_add_u64 v[10:11], v[36:37], 0, s[38:39]
	v_lshl_add_u64 v[12:13], v[130:131], 0, v[12:13]
	v_lshlrev_b64 v[10:11], 11, v[10:11]
	s_mov_b32 s38, 0x2000
	s_mov_b32 s39, 0
	v_lshl_add_u64 v[10:11], v[130:131], 0, v[10:11]
	v_lshl_add_u64 v[14:15], v[12:13], 0, s[38:39]
	v_lshl_add_u64 v[8:9], v[10:11], 0, s[38:39]
	global_load_dwordx4 v[244:247], v[12:13], off
	global_load_dwordx4 v[32:35], v[12:13], off offset:64
	global_load_dwordx4 v[28:31], v[14:15], off
	global_load_dwordx4 v[24:27], v[14:15], off offset:64
	global_load_dwordx4 v[20:23], v[10:11], off
	global_load_dwordx4 v[16:19], v[10:11], off offset:64
	global_load_dwordx4 v[12:15], v[8:9], off
	global_load_dwordx4 v[8:11], v[8:9], off offset:64
	s_waitcnt vmcnt(23)
	v_mfma_f32_16x16x32_bf16 v[184:187], v[184:187], v[4:7], 0
	s_waitcnt vmcnt(22)
	v_mfma_f32_16x16x32_bf16 v[188:191], v[188:191], v[0:3], v[184:187]
	s_nop 7
	v_fmac_f32_e32 v85, 0x3e000000, v188
	v_cndmask_b32_e64 v85, v227, v85, s[22:23]
	v_fmac_f32_e32 v84, 0x3e000000, v189
	v_cndmask_b32_e64 v84, v227, v84, s[24:25]
	v_fmac_f32_e32 v87, 0x3e000000, v190
	v_cndmask_b32_e64 v87, v227, v87, s[26:27]
	v_fmac_f32_e32 v86, 0x3e000000, v191
	v_cndmask_b32_e64 v86, v227, v86, s[28:29]
	s_waitcnt vmcnt(21)
	v_mfma_f32_16x16x32_bf16 v[192:195], v[192:195], v[4:7], 0
	s_waitcnt vmcnt(20)
	v_mfma_f32_16x16x32_bf16 v[196:199], v[196:199], v[0:3], v[192:195]
	s_nop 7
	v_fmac_f32_e32 v89, 0x3e000000, v196
	v_cndmask_b32_e64 v89, v227, v89, s[30:31]
	v_fmac_f32_e32 v88, 0x3e000000, v197
	v_cndmask_b32_e64 v88, v227, v88, s[34:35]
	v_fmac_f32_e32 v91, 0x3e000000, v198
	v_cndmask_b32_e64 v91, v227, v91, s[36:37]
	v_fmac_f32_e32 v90, 0x3e000000, v199
	v_cndmask_b32_e64 v90, v227, v90, s[6:7]
	s_waitcnt vmcnt(19)
; __device__ __forceinline__ f32x4 mfma16(bf16x8 a, bf16x8 b, f32x4 c) { return __builtin_amdgcn_mfma_f32_16x16x32_bf16(a, b, c, 0, 0, 0); }
; __device__ __forceinline__ void phase_attn(const Args& a, unsigned char* smem, int tid, int lane, int wave, bf16_t* Yout) {
;     ...
;                     const float* rp = rpb_s + (rs + i - r + 7) * 31;
; #pragma unroll
;                     for (int hf = 0; hf < 2; ++hf) {
;                         f32x4 s = {0.f, 0.f, 0.f, 0.f};
;                         s = mfma16(kbuf[0][(ii * 2 + hf) * 2], qf0, s); s = mfma16(kbuf[0][(ii * 2 + hf) * 2 + 1], qf1, s);
; #pragma unroll
;                         for (int e = 0; e < 4; ++e) { const int kc = kc0 + 8 * g + 4 * hf + e; const bool ok = (kc >= cs) && (kc < cs + 16);
;                             const int dc = min(max(kc - qc + 15, 0), 30);
;                             s[e] = ok ? s[e] * 0.125f + rp[dc] : -1e30f; }
;                         st[i * 2 + hf] = s;
;                     }
	v_mfma_f32_16x16x32_bf16 v[200:203], v[200:203], v[4:7], 0
	s_waitcnt vmcnt(18)
	v_mfma_f32_16x16x32_bf16 v[204:207], v[204:207], v[0:3], v[200:203]
	s_nop 7
	v_fmac_f32_e32 v93, 0x3e000000, v204
	v_cndmask_b32_e64 v93, v227, v93, s[22:23]
	v_fmac_f32_e32 v92, 0x3e000000, v205
	v_cndmask_b32_e64 v92, v227, v92, s[24:25]
	v_fmac_f32_e32 v95, 0x3e000000, v206
	v_cndmask_b32_e64 v95, v227, v95, s[26:27]
	v_fmac_f32_e32 v94, 0x3e000000, v207
	v_cndmask_b32_e64 v94, v227, v94, s[28:29]
	s_waitcnt vmcnt(17)
	v_mfma_f32_16x16x32_bf16 v[208:211], v[208:211], v[4:7], 0
	s_waitcnt vmcnt(16)
	v_mfma_f32_16x16x32_bf16 v[212:215], v[212:215], v[0:3], v[208:211]
	s_nop 7
	v_fmac_f32_e32 v97, 0x3e000000, v212
	v_cndmask_b32_e64 v97, v227, v97, s[30:31]
	v_fmac_f32_e32 v96, 0x3e000000, v213
	v_cndmask_b32_e64 v96, v227, v96, s[34:35]
	v_fmac_f32_e32 v99, 0x3e000000, v214
	v_cndmask_b32_e64 v99, v227, v99, s[36:37]
	v_fmac_f32_e32 v98, 0x3e000000, v215
	v_cndmask_b32_e64 v98, v227, v98, s[6:7]
	s_waitcnt vmcnt(15)
	v_mfma_f32_16x16x32_bf16 v[52:55], v[52:55], v[4:7], 0
	s_waitcnt vmcnt(14)
	v_mfma_f32_16x16x32_bf16 v[56:59], v[56:59], v[0:3], v[52:55]
	s_nop 7
	v_fmac_f32_e32 v101, 0x3e000000, v56
	v_cndmask_b32_e64 v101, v227, v101, s[22:23]
	v_fmac_f32_e32 v100, 0x3e000000, v57
	v_cndmask_b32_e64 v100, v227, v100, s[24:25]
	v_fmac_f32_e32 v103, 0x3e000000, v58
	v_cndmask_b32_e64 v103, v227, v103, s[26:27]
	v_fmac_f32_e32 v102, 0x3e000000, v59
	v_cndmask_b32_e64 v102, v227, v102, s[28:29]
	s_waitcnt vmcnt(13)
	v_mfma_f32_16x16x32_bf16 v[60:63], v[60:63], v[4:7], 0
	s_waitcnt vmcnt(12)
	v_mfma_f32_16x16x32_bf16 v[64:67], v[64:67], v[0:3], v[60:63]
	s_nop 7
	v_fmac_f32_e32 v105, 0x3e000000, v64
	v_cndmask_b32_e64 v105, v227, v105, s[30:31]
	v_fmac_f32_e32 v104, 0x3e000000, v65
	v_cndmask_b32_e64 v104, v227, v104, s[34:35]
	v_fmac_f32_e32 v107, 0x3e000000, v66
	v_cndmask_b32_e64 v107, v227, v107, s[36:37]
	v_fmac_f32_e32 v106, 0x3e000000, v67
	v_cndmask_b32_e64 v106, v227, v106, s[6:7]
	s_waitcnt vmcnt(11)
	v_mfma_f32_16x16x32_bf16 v[228:231], v[228:231], v[4:7], 0
	s_waitcnt vmcnt(10)
	v_mfma_f32_16x16x32_bf16 v[232:235], v[232:235], v[0:3], v[228:231]
	s_nop 7
	v_fmac_f32_e32 v109, 0x3e000000, v232
	v_cndmask_b32_e64 v109, v227, v109, s[22:23]
	v_fmac_f32_e32 v108, 0x3e000000, v233
	v_cndmask_b32_e64 v108, v227, v108, s[24:25]
	v_fmac_f32_e32 v111, 0x3e000000, v234
	v_cndmask_b32_e64 v111, v227, v111, s[26:27]
	v_fmac_f32_e32 v110, 0x3e000000, v235
	v_cndmask_b32_e64 v110, v227, v110, s[28:29]
	s_waitcnt vmcnt(9)
	v_mfma_f32_16x16x32_bf16 v[236:239], v[236:239], v[4:7], 0
	s_waitcnt vmcnt(8)
	v_mfma_f32_16x16x32_bf16 v[240:243], v[240:243], v[0:3], v[236:239]
	s_nop 7
	v_fmac_f32_e32 v148, 0x3e000000, v240
	v_cndmask_b32_e64 v148, v227, v148, s[30:31]
	v_fmac_f32_e32 v147, 0x3e000000, v241
	v_cndmask_b32_e64 v147, v227, v147, s[34:35]
	v_fmac_f32_e32 v150, 0x3e000000, v242
	v_cndmask_b32_e64 v150, v227, v150, s[36:37]
	v_fmac_f32_e32 v149, 0x3e000000, v243
	v_cndmask_b32_e64 v149, v227, v149, s[6:7]
	s_waitcnt vmcnt(7)
	v_mfma_f32_16x16x32_bf16 v[244:247], v[244:247], v[4:7], 0
	s_waitcnt vmcnt(6)
	v_mfma_f32_16x16x32_bf16 v[32:35], v[32:35], v[0:3], v[244:247]
	s_nop 7
	v_fmac_f32_e32 v152, 0x3e000000, v32
	v_cndmask_b32_e64 v152, v227, v152, s[22:23]
	v_fmac_f32_e32 v151, 0x3e000000, v33
	v_cndmask_b32_e64 v151, v227, v151, s[24:25]
	v_fmac_f32_e32 v154, 0x3e000000, v34
	v_cndmask_b32_e64 v154, v227, v154, s[26:27]
	v_fmac_f32_e32 v153, 0x3e000000, v35
	v_cndmask_b32_e64 v153, v227, v153, s[28:29]
	s_waitcnt vmcnt(5)
	v_mfma_f32_16x16x32_bf16 v[28:31], v[28:31], v[4:7], 0
	s_waitcnt vmcnt(4)
	v_mfma_f32_16x16x32_bf16 v[24:27], v[24:27], v[0:3], v[28:31]
	s_nop 7
	v_fmac_f32_e32 v216, 0x3e000000, v24
	v_cndmask_b32_e64 v216, v227, v216, s[30:31]
	v_fmac_f32_e32 v155, 0x3e000000, v25
	v_cndmask_b32_e64 v155, v227, v155, s[34:35]
	v_fmac_f32_e32 v218, 0x3e000000, v26
	v_cndmask_b32_e64 v218, v227, v218, s[36:37]
	v_fmac_f32_e32 v217, 0x3e000000, v27
	v_cndmask_b32_e64 v217, v227, v217, s[6:7]
	s_waitcnt vmcnt(3)
	v_mfma_f32_16x16x32_bf16 v[20:23], v[20:23], v[4:7], 0
	s_waitcnt vmcnt(2)
	v_mfma_f32_16x16x32_bf16 v[16:19], v[16:19], v[0:3], v[20:23]
	s_nop 7
	v_fmac_f32_e32 v220, 0x3e000000, v16
	v_cndmask_b32_e64 v220, v227, v220, s[22:23]
	v_fmac_f32_e32 v219, 0x3e000000, v17
	v_cndmask_b32_e64 v219, v227, v219, s[24:25]
	v_fmac_f32_e32 v222, 0x3e000000, v18
	v_cndmask_b32_e64 v222, v227, v222, s[26:27]
	v_fmac_f32_e32 v221, 0x3e000000, v19
	v_cndmask_b32_e64 v221, v227, v221, s[28:29]
	s_waitcnt vmcnt(1)
	v_mfma_f32_16x16x32_bf16 v[12:15], v[12:15], v[4:7], 0
	s_waitcnt vmcnt(0)
	v_mfma_f32_16x16x32_bf16 v[8:11], v[8:11], v[0:3], v[12:15]
	s_nop 7
	v_fmac_f32_e32 v224, 0x3e000000, v8
	v_cndmask_b32_e64 v224, v227, v224, s[30:31]
	v_fmac_f32_e32 v223, 0x3e000000, v9
	v_cndmask_b32_e64 v223, v227, v223, s[34:35]
	v_mov_b32_e32 v225, 0xf149f2ca
	v_fmac_f32_e32 v226, 0x3e000000, v10
	v_cndmask_b32_e64 v226, v227, v226, s[36:37]
	s_and_saveexec_b64 s[22:23], s[6:7]
	s_cbranch_execz .LBB0_334
	v_add_u32_e32 v8, 15, v45
	v_min_u32_e32 v8, 30, v8
	v_lshl_add_u32 v8, v8, 2, s1
	ds_read_b32 v225, v8 offset:1736
	s_waitcnt lgkmcnt(0)
	v_fmac_f32_e32 v225, 0x3e000000, v11
	s_branch .LBB0_334
